# epilogue rms factor: v_rsq_f32 + one Newton step (f32) instead of compiled sqrt+IEEE-div chain in L1/L7/L13 epilogues
# speedup vs baseline: 1.1029x; 1.0018x over previous
.LBB0_106:
	v_lshl_add_u32 v142, s56, 8, v152
	v_ashrrev_i32_e32 v143, 31, v142
	v_lshlrev_b64 v[144:145], 6, v[142:143]
	v_lshl_add_u64 v[150:151], s[18:19], 0, v[144:145]
	global_load_dwordx4 v[146:149], v[150:151], off
	global_load_dwordx4 v[156:159], v[150:151], off offset:16
	global_load_dwordx4 v[160:163], v[150:151], off offset:32
	global_load_dwordx4 v[164:167], v[150:151], off offset:48
	s_lshl_b32 s4, s6, 8
	s_or_b32 s49, s4, s66
	s_mov_b64 s[6:7], 0
	s_waitcnt vmcnt(0)
	v_pk_add_f32 v[148:149], v[148:149], v[158:159]
	v_pk_add_f32 v[146:147], v[146:147], v[156:157]
	v_pk_add_f32 v[150:151], v[162:163], v[166:167]
	v_pk_add_f32 v[156:157], v[160:161], v[164:165]
	v_pk_add_f32 v[148:149], v[148:149], v[150:151]
	v_pk_add_f32 v[146:147], v[146:147], v[156:157]
	v_or_b32_e32 v156, s49, v153
	v_pk_mov_b32 v[150:151], v[146:147], v[148:149] op_sel:[1,0]
	v_mov_b32_e32 v147, v149
	v_pk_add_f32 v[146:147], v[150:151], v[146:147]
	s_nop 0
	v_add_f32_e32 v146, v146, v147
	v_fmamk_f32 v146, v146, 0x3a800000, v212
	v_rsq_f32_e32 v250, v146
	s_nop 0
	v_mul_f32_e32 v251, v146, v250
	v_fma_f32 v251, -v251, v250, 1.0
	v_mul_f32_e32 v252, 0.5, v250
	s_nop 0
	v_cmp_lt_i32_e64 s[4:5], s75, v156
	v_fma_f32 v146, v252, v251, v250
	v_pk_mul_f32 v[128:129], v[128:129], v[146:147] op_sel_hi:[1,0]
	v_pk_mul_f32 v[148:149], v[124:125], v[146:147] op_sel_hi:[1,0]
	v_pk_mul_f32 v[124:125], v[122:123], v[146:147] op_sel_hi:[1,0]
	v_pk_mul_f32 v[126:127], v[126:127], v[146:147] op_sel_hi:[1,0]
	s_nop 0
	v_cvt_pk_bf16_f32 v122, v126, v127
	v_cvt_pk_bf16_f32 v123, v128, v129
	v_cvt_pk_bf16_f32 v124, v124, v125
	v_cvt_pk_bf16_f32 v125, v148, v149
	s_and_saveexec_b64 s[8:9], s[4:5]
	s_xor_b64 s[8:9], exec, s[8:9]
	s_cbranch_execz .LBB0_110
	s_cmpk_lt_u32 s49, 0x820
	s_cbranch_scc0 .LBB0_109
	v_lshl_add_u64 v[128:129], s[44:45], 0, v[144:145]
	v_add_u32_e32 v148, 0xfffff800, v156
	s_mov_b64 s[6:7], -1

.LBB0_118:
	s_or_b64 exec, exec, s[54:55]
	s_nop 0
	v_or_b32_e32 v116, 16, v142
	v_ashrrev_i32_e32 v117, 31, v116
	v_lshlrev_b64 v[114:115], 6, v[116:117]
	v_lshl_add_u64 v[128:129], s[18:19], 0, v[114:115]
	global_load_dwordx4 v[120:123], v[128:129], off
	global_load_dwordx4 v[124:127], v[128:129], off offset:16
	global_load_dwordx4 v[144:147], v[128:129], off offset:32
	global_load_dwordx4 v[148:151], v[128:129], off offset:48
	s_waitcnt vmcnt(2)
	v_pk_add_f32 v[122:123], v[122:123], v[126:127]
	v_pk_add_f32 v[120:121], v[120:121], v[124:125]
	s_waitcnt vmcnt(0)
	v_pk_add_f32 v[124:125], v[146:147], v[150:151]
	v_pk_add_f32 v[126:127], v[144:145], v[148:149]
	v_pk_add_f32 v[122:123], v[122:123], v[124:125]
	v_pk_add_f32 v[120:121], v[120:121], v[126:127]
	s_nop 0
	v_pk_mov_b32 v[124:125], v[120:121], v[122:123] op_sel:[1,0]
	v_mov_b32_e32 v121, v123
	v_pk_add_f32 v[120:121], v[124:125], v[120:121]
	s_nop 0
	v_add_f32_e32 v119, v120, v121
	v_fmamk_f32 v119, v119, 0x3a800000, v212
	v_rsq_f32_e32 v250, v119
	s_nop 0
	v_mul_f32_e32 v251, v119, v250
	v_fma_f32 v251, -v251, v250, 1.0
	v_mul_f32_e32 v252, 0.5, v250
	s_nop 0
	s_mov_b64 s[8:9], 0
	v_fma_f32 v120, v252, v251, v250
	v_pk_mul_f32 v[112:113], v[112:113], v[120:121] op_sel_hi:[1,0]
	v_pk_mul_f32 v[122:123], v[108:109], v[120:121] op_sel_hi:[1,0]
	v_pk_mul_f32 v[108:109], v[106:107], v[120:121] op_sel_hi:[1,0]
	v_pk_mul_f32 v[110:111], v[110:111], v[120:121] op_sel_hi:[1,0]
	s_nop 0
	v_cvt_pk_bf16_f32 v106, v110, v111
	v_cvt_pk_bf16_f32 v107, v112, v113
	v_cvt_pk_bf16_f32 v108, v108, v109
	v_cvt_pk_bf16_f32 v109, v122, v123
	s_and_saveexec_b64 s[20:21], s[4:5]
	s_xor_b64 s[54:55], exec, s[20:21]
	s_cbranch_execz .LBB0_122
	s_cmpk_lt_u32 s49, 0x820
	s_cbranch_scc0 .LBB0_121
	v_lshl_add_u64 v[112:113], s[44:45], 0, v[114:115]
	v_add_u32_e32 v122, 0xfffff800, v156
	s_mov_b64 s[8:9], -1

.LBB0_130:
	s_or_b64 exec, exec, s[54:55]
	s_nop 0
	v_or_b32_e32 v100, 32, v142
	v_ashrrev_i32_e32 v101, 31, v100
	v_lshlrev_b64 v[98:99], 6, v[100:101]
	v_lshl_add_u64 v[114:115], s[18:19], 0, v[98:99]
	global_load_dwordx4 v[102:105], v[114:115], off
	global_load_dwordx4 v[106:109], v[114:115], off offset:16
	global_load_dwordx4 v[110:113], v[114:115], off offset:32
	s_nop 0
	global_load_dwordx4 v[114:117], v[114:115], off offset:48
	s_waitcnt vmcnt(2)
	v_pk_add_f32 v[104:105], v[104:105], v[108:109]
	v_pk_add_f32 v[102:103], v[102:103], v[106:107]
	s_waitcnt vmcnt(0)
	v_pk_add_f32 v[106:107], v[112:113], v[116:117]
	v_pk_add_f32 v[108:109], v[110:111], v[114:115]
	v_pk_add_f32 v[104:105], v[104:105], v[106:107]
	v_pk_add_f32 v[102:103], v[102:103], v[108:109]
	s_nop 0
	v_pk_mov_b32 v[106:107], v[102:103], v[104:105] op_sel:[1,0]
	v_mov_b32_e32 v103, v105
	v_pk_add_f32 v[102:103], v[106:107], v[102:103]
	s_nop 0
	v_add_f32_e32 v102, v102, v103
	v_fmamk_f32 v102, v102, 0x3a800000, v212
	v_rsq_f32_e32 v250, v102
	s_nop 0
	v_mul_f32_e32 v251, v102, v250
	v_fma_f32 v251, -v251, v250, 1.0
	v_mul_f32_e32 v252, 0.5, v250
	s_nop 0
	s_mov_b64 s[8:9], 0
	v_fma_f32 v102, v252, v251, v250
	v_pk_mul_f32 v[96:97], v[96:97], v[102:103] op_sel_hi:[1,0]
	v_pk_mul_f32 v[104:105], v[92:93], v[102:103] op_sel_hi:[1,0]
	v_pk_mul_f32 v[92:93], v[90:91], v[102:103] op_sel_hi:[1,0]
	v_pk_mul_f32 v[94:95], v[94:95], v[102:103] op_sel_hi:[1,0]
	s_nop 0
	v_cvt_pk_bf16_f32 v90, v94, v95
	v_cvt_pk_bf16_f32 v91, v96, v97
	v_cvt_pk_bf16_f32 v92, v92, v93
	v_cvt_pk_bf16_f32 v93, v104, v105
	s_and_saveexec_b64 s[20:21], s[4:5]
	s_xor_b64 s[54:55], exec, s[20:21]
	s_cbranch_execz .LBB0_134
	s_cmpk_lt_u32 s49, 0x820
	s_cbranch_scc0 .LBB0_133
	v_lshl_add_u64 v[96:97], s[44:45], 0, v[98:99]
	v_add_u32_e32 v104, 0xfffff800, v156
	s_mov_b64 s[8:9], -1

.LBB0_142:
	s_or_b64 exec, exec, s[54:55]
	s_nop 0
	v_or_b32_e32 v84, 48, v142
	v_ashrrev_i32_e32 v85, 31, v84
	v_lshlrev_b64 v[82:83], 6, v[84:85]
	v_lshl_add_u64 v[98:99], s[18:19], 0, v[82:83]
	global_load_dwordx4 v[86:89], v[98:99], off
	global_load_dwordx4 v[90:93], v[98:99], off offset:16
	global_load_dwordx4 v[94:97], v[98:99], off offset:32
	s_nop 0
	global_load_dwordx4 v[98:101], v[98:99], off offset:48
	s_waitcnt vmcnt(2)
	v_pk_add_f32 v[88:89], v[88:89], v[92:93]
	v_pk_add_f32 v[86:87], v[86:87], v[90:91]
	s_waitcnt vmcnt(0)
	v_pk_add_f32 v[90:91], v[96:97], v[100:101]
	v_pk_add_f32 v[92:93], v[94:95], v[98:99]
	v_pk_add_f32 v[88:89], v[88:89], v[90:91]
	v_pk_add_f32 v[86:87], v[86:87], v[92:93]
	s_nop 0
	v_pk_mov_b32 v[90:91], v[86:87], v[88:89] op_sel:[1,0]
	v_mov_b32_e32 v87, v89
	v_pk_add_f32 v[86:87], v[90:91], v[86:87]
	s_nop 0
	v_add_f32_e32 v86, v86, v87
	v_fmamk_f32 v86, v86, 0x3a800000, v212
	v_rsq_f32_e32 v250, v86
	s_nop 0
	v_mul_f32_e32 v251, v86, v250
	v_fma_f32 v251, -v251, v250, 1.0
	v_mul_f32_e32 v252, 0.5, v250
	s_nop 0
	s_mov_b64 s[8:9], 0
	v_fma_f32 v86, v252, v251, v250
	v_pk_mul_f32 v[80:81], v[80:81], v[86:87] op_sel_hi:[1,0]
	v_pk_mul_f32 v[88:89], v[76:77], v[86:87] op_sel_hi:[1,0]
	v_pk_mul_f32 v[76:77], v[74:75], v[86:87] op_sel_hi:[1,0]
	v_pk_mul_f32 v[78:79], v[78:79], v[86:87] op_sel_hi:[1,0]
	s_nop 0
	v_cvt_pk_bf16_f32 v74, v78, v79
	v_cvt_pk_bf16_f32 v75, v80, v81
	v_cvt_pk_bf16_f32 v76, v76, v77
	v_cvt_pk_bf16_f32 v77, v88, v89
	s_and_saveexec_b64 s[20:21], s[4:5]
	s_xor_b64 s[54:55], exec, s[20:21]
	s_cbranch_execz .LBB0_146
	s_cmpk_lt_u32 s49, 0x820
	s_cbranch_scc0 .LBB0_145
	v_lshl_add_u64 v[80:81], s[44:45], 0, v[82:83]
	v_add_u32_e32 v88, 0xfffff800, v156
	s_mov_b64 s[8:9], -1

.LBB0_154:
	s_or_b64 exec, exec, s[54:55]
	s_nop 0
	v_add_u32_e32 v68, 0x80, v142
	v_ashrrev_i32_e32 v69, 31, v68
	v_lshlrev_b64 v[66:67], 6, v[68:69]
	v_lshl_add_u64 v[82:83], s[18:19], 0, v[66:67]
	global_load_dwordx4 v[70:73], v[82:83], off
	global_load_dwordx4 v[74:77], v[82:83], off offset:16
	global_load_dwordx4 v[78:81], v[82:83], off offset:32
	s_nop 0
	global_load_dwordx4 v[82:85], v[82:83], off offset:48
	s_waitcnt vmcnt(2)
	v_pk_add_f32 v[72:73], v[72:73], v[76:77]
	v_pk_add_f32 v[70:71], v[70:71], v[74:75]
	s_waitcnt vmcnt(0)
	v_pk_add_f32 v[74:75], v[80:81], v[84:85]
	v_pk_add_f32 v[76:77], v[78:79], v[82:83]
	v_pk_add_f32 v[72:73], v[72:73], v[74:75]
	v_pk_add_f32 v[70:71], v[70:71], v[76:77]
	s_nop 0
	v_pk_mov_b32 v[74:75], v[70:71], v[72:73] op_sel:[1,0]
	v_mov_b32_e32 v71, v73
	v_pk_add_f32 v[70:71], v[74:75], v[70:71]
	s_nop 0
	v_add_f32_e32 v70, v70, v71
	v_fmamk_f32 v70, v70, 0x3a800000, v212
	v_rsq_f32_e32 v250, v70
	s_nop 0
	v_mul_f32_e32 v251, v70, v250
	v_fma_f32 v251, -v251, v250, 1.0
	v_mul_f32_e32 v252, 0.5, v250
	s_nop 0
	s_mov_b64 s[8:9], 0
	v_fma_f32 v70, v252, v251, v250
	v_pk_mul_f32 v[64:65], v[64:65], v[70:71] op_sel_hi:[1,0]
	v_pk_mul_f32 v[72:73], v[60:61], v[70:71] op_sel_hi:[1,0]
	v_pk_mul_f32 v[60:61], v[58:59], v[70:71] op_sel_hi:[1,0]
	v_pk_mul_f32 v[62:63], v[62:63], v[70:71] op_sel_hi:[1,0]
	s_nop 0
	v_cvt_pk_bf16_f32 v58, v62, v63
	v_cvt_pk_bf16_f32 v59, v64, v65
	v_cvt_pk_bf16_f32 v60, v60, v61
	v_cvt_pk_bf16_f32 v61, v72, v73
	s_and_saveexec_b64 s[20:21], s[4:5]
	s_xor_b64 s[54:55], exec, s[20:21]
	s_cbranch_execz .LBB0_158
	s_cmpk_lt_u32 s49, 0x820
	s_cbranch_scc0 .LBB0_157
	v_lshl_add_u64 v[64:65], s[44:45], 0, v[66:67]
	v_add_u32_e32 v72, 0xfffff800, v156
	s_mov_b64 s[8:9], -1

.LBB0_166:
	s_or_b64 exec, exec, s[54:55]
	s_nop 0
	v_add_u32_e32 v52, 0x90, v142
	v_ashrrev_i32_e32 v53, 31, v52
	v_lshlrev_b64 v[50:51], 6, v[52:53]
	v_lshl_add_u64 v[66:67], s[18:19], 0, v[50:51]
	global_load_dwordx4 v[54:57], v[66:67], off
	global_load_dwordx4 v[58:61], v[66:67], off offset:16
	global_load_dwordx4 v[62:65], v[66:67], off offset:32
	s_nop 0
	global_load_dwordx4 v[66:69], v[66:67], off offset:48
	s_waitcnt vmcnt(2)
	v_pk_add_f32 v[56:57], v[56:57], v[60:61]
	v_pk_add_f32 v[54:55], v[54:55], v[58:59]
	s_waitcnt vmcnt(0)
	v_pk_add_f32 v[58:59], v[64:65], v[68:69]
	v_pk_add_f32 v[60:61], v[62:63], v[66:67]
	v_pk_add_f32 v[56:57], v[56:57], v[58:59]
	v_pk_add_f32 v[54:55], v[54:55], v[60:61]
	s_nop 0
	v_pk_mov_b32 v[58:59], v[54:55], v[56:57] op_sel:[1,0]
	v_mov_b32_e32 v55, v57
	v_pk_add_f32 v[54:55], v[58:59], v[54:55]
	s_nop 0
	v_add_f32_e32 v54, v54, v55
	v_fmamk_f32 v54, v54, 0x3a800000, v212
	v_rsq_f32_e32 v250, v54
	s_nop 0
	v_mul_f32_e32 v251, v54, v250
	v_fma_f32 v251, -v251, v250, 1.0
	v_mul_f32_e32 v252, 0.5, v250
	s_nop 0
	s_mov_b64 s[8:9], 0
	v_fma_f32 v54, v252, v251, v250
	v_pk_mul_f32 v[48:49], v[48:49], v[54:55] op_sel_hi:[1,0]
	v_pk_mul_f32 v[56:57], v[44:45], v[54:55] op_sel_hi:[1,0]
	v_pk_mul_f32 v[44:45], v[42:43], v[54:55] op_sel_hi:[1,0]
	v_pk_mul_f32 v[46:47], v[46:47], v[54:55] op_sel_hi:[1,0]
	s_nop 0
	v_cvt_pk_bf16_f32 v42, v46, v47
	v_cvt_pk_bf16_f32 v43, v48, v49
	v_cvt_pk_bf16_f32 v44, v44, v45
	v_cvt_pk_bf16_f32 v45, v56, v57
	s_and_saveexec_b64 s[20:21], s[4:5]
	s_xor_b64 s[54:55], exec, s[20:21]
	s_cbranch_execz .LBB0_170
	s_cmpk_lt_u32 s49, 0x820
	s_cbranch_scc0 .LBB0_169
	v_lshl_add_u64 v[48:49], s[44:45], 0, v[50:51]
	v_add_u32_e32 v56, 0xfffff800, v156
	s_mov_b64 s[8:9], -1

.LBB0_178:
	s_or_b64 exec, exec, s[54:55]
	s_nop 0
	v_add_u32_e32 v36, 0xa0, v142
	v_ashrrev_i32_e32 v37, 31, v36
	v_lshlrev_b64 v[34:35], 6, v[36:37]
	v_lshl_add_u64 v[50:51], s[18:19], 0, v[34:35]
	global_load_dwordx4 v[38:41], v[50:51], off
	global_load_dwordx4 v[42:45], v[50:51], off offset:16
	global_load_dwordx4 v[46:49], v[50:51], off offset:32
	s_nop 0
	global_load_dwordx4 v[50:53], v[50:51], off offset:48
	s_waitcnt vmcnt(2)
	v_pk_add_f32 v[40:41], v[40:41], v[44:45]
	v_pk_add_f32 v[38:39], v[38:39], v[42:43]
	s_waitcnt vmcnt(0)
	v_pk_add_f32 v[42:43], v[48:49], v[52:53]
	v_pk_add_f32 v[44:45], v[46:47], v[50:51]
	v_pk_add_f32 v[40:41], v[40:41], v[42:43]
	v_pk_add_f32 v[38:39], v[38:39], v[44:45]
	s_nop 0
	v_pk_mov_b32 v[42:43], v[38:39], v[40:41] op_sel:[1,0]
	v_mov_b32_e32 v39, v41
	v_pk_add_f32 v[38:39], v[42:43], v[38:39]
	s_nop 0
	v_add_f32_e32 v38, v38, v39
	v_fmamk_f32 v38, v38, 0x3a800000, v212
	v_rsq_f32_e32 v250, v38
	s_nop 0
	v_mul_f32_e32 v251, v38, v250
	v_fma_f32 v251, -v251, v250, 1.0
	v_mul_f32_e32 v252, 0.5, v250
	s_nop 0
	s_mov_b64 s[8:9], 0
	v_fma_f32 v38, v252, v251, v250
	v_pk_mul_f32 v[32:33], v[32:33], v[38:39] op_sel_hi:[1,0]
	v_pk_mul_f32 v[40:41], v[28:29], v[38:39] op_sel_hi:[1,0]
	v_pk_mul_f32 v[28:29], v[26:27], v[38:39] op_sel_hi:[1,0]
	v_pk_mul_f32 v[30:31], v[30:31], v[38:39] op_sel_hi:[1,0]
	s_nop 0
	v_cvt_pk_bf16_f32 v26, v30, v31
	v_cvt_pk_bf16_f32 v27, v32, v33
	v_cvt_pk_bf16_f32 v28, v28, v29
	v_cvt_pk_bf16_f32 v29, v40, v41
	s_and_saveexec_b64 s[20:21], s[4:5]
	s_xor_b64 s[54:55], exec, s[20:21]
	s_cbranch_execz .LBB0_182
	s_cmpk_lt_u32 s49, 0x820
	s_cbranch_scc0 .LBB0_181
	v_lshl_add_u64 v[32:33], s[44:45], 0, v[34:35]
	v_add_u32_e32 v40, 0xfffff800, v156
	s_mov_b64 s[8:9], -1

.LBB0_190:
	s_or_b64 exec, exec, s[54:55]
	s_nop 0
	v_add_u32_e32 v20, 0xb0, v142
	v_ashrrev_i32_e32 v21, 31, v20
	v_lshlrev_b64 v[18:19], 6, v[20:21]
	v_lshl_add_u64 v[34:35], s[18:19], 0, v[18:19]
	global_load_dwordx4 v[22:25], v[34:35], off
	global_load_dwordx4 v[26:29], v[34:35], off offset:16
	global_load_dwordx4 v[30:33], v[34:35], off offset:32
	s_nop 0
	global_load_dwordx4 v[34:37], v[34:35], off offset:48
	s_waitcnt vmcnt(2)
	v_pk_add_f32 v[24:25], v[24:25], v[28:29]
	v_pk_add_f32 v[22:23], v[22:23], v[26:27]
	s_waitcnt vmcnt(0)
	v_pk_add_f32 v[26:27], v[32:33], v[36:37]
	v_pk_add_f32 v[28:29], v[30:31], v[34:35]
	v_pk_add_f32 v[24:25], v[24:25], v[26:27]
	v_pk_add_f32 v[22:23], v[22:23], v[28:29]
	s_nop 0
	v_pk_mov_b32 v[26:27], v[22:23], v[24:25] op_sel:[1,0]
	v_mov_b32_e32 v23, v25
	v_pk_add_f32 v[22:23], v[26:27], v[22:23]
	s_nop 0
	v_add_f32_e32 v22, v22, v23
	v_fmamk_f32 v22, v22, 0x3a800000, v212
	v_rsq_f32_e32 v250, v22
	s_nop 0
	v_mul_f32_e32 v251, v22, v250
	v_fma_f32 v251, -v251, v250, 1.0
	v_mul_f32_e32 v252, 0.5, v250
	s_nop 0
	s_mov_b64 s[8:9], 0
	v_fma_f32 v22, v252, v251, v250
	v_pk_mul_f32 v[16:17], v[16:17], v[22:23] op_sel_hi:[1,0]
	v_pk_mul_f32 v[24:25], v[12:13], v[22:23] op_sel_hi:[1,0]
	v_pk_mul_f32 v[12:13], v[10:11], v[22:23] op_sel_hi:[1,0]
	v_pk_mul_f32 v[14:15], v[14:15], v[22:23] op_sel_hi:[1,0]
	s_nop 0
	v_cvt_pk_bf16_f32 v10, v14, v15
	v_cvt_pk_bf16_f32 v11, v16, v17
	v_cvt_pk_bf16_f32 v12, v12, v13
	v_cvt_pk_bf16_f32 v13, v24, v25
	s_and_saveexec_b64 s[20:21], s[4:5]
	s_xor_b64 s[4:5], exec, s[20:21]
	s_cbranch_execz .LBB0_194
	s_cmpk_lt_u32 s49, 0x820
	s_cbranch_scc0 .LBB0_193
	v_lshl_add_u64 v[16:17], s[44:45], 0, v[18:19]
	v_add_u32_e32 v24, 0xfffff800, v156
	s_mov_b64 s[8:9], -1

.LBB0_2151:
	s_ashr_i32 s47, s46, 31
	s_lshl_b64 s[4:5], s[46:47], 8
	v_mov_b32_e32 v176, v172
	v_mov_b32_e32 v160, v173
	s_add_u32 s4, s4, s60
	s_addc_u32 s5, s5, s64
	v_ashrrev_i32_e32 v161, 31, v160
	v_lshl_add_u64 v[140:141], s[4:5], 0, v[160:161]
	v_lshlrev_b64 v[140:141], 6, v[140:141]
	v_lshl_add_u64 v[142:143], s[10:11], 0, v[140:141]
	global_load_dwordx4 v[144:147], v[142:143], off
	global_load_dwordx4 v[148:151], v[142:143], off offset:16
	global_load_dwordx4 v[152:155], v[142:143], off offset:32
	global_load_dwordx4 v[156:159], v[142:143], off offset:48
	v_lshlrev_b32_e32 v162, 2, v160
	s_waitcnt vmcnt(0)
	v_pk_add_f32 v[140:141], v[146:147], v[150:151]
	v_pk_add_f32 v[144:145], v[144:145], v[148:149]
	v_pk_add_f32 v[146:147], v[154:155], v[158:159]
	v_pk_add_f32 v[148:149], v[152:153], v[156:157]
	v_pk_add_f32 v[140:141], v[140:141], v[146:147]
	v_pk_add_f32 v[144:145], v[144:145], v[148:149]
	s_nop 0
	v_pk_mov_b32 v[146:147], v[144:145], v[140:141] op_sel:[1,0]
	v_mov_b32_e32 v145, v141
	v_pk_add_f32 v[140:141], v[146:147], v[144:145]
	v_lshl_add_u32 v145, v176, 6, v162
	v_add_f32_e32 v140, v140, v141
	v_fmamk_f32 v140, v140, 0x3a800000, v212
	v_rsq_f32_e32 v224, v140
	s_nop 0
	v_mul_f32_e32 v225, v140, v224
	v_fma_f32 v225, -v225, v224, 1.0
	v_mul_f32_e32 v226, 0.5, v224
	v_xor_b32_e32 v177, 64, v145
	s_nop 0
	s_nop 0
	v_cmp_eq_u32_e64 s[4:5], 0, v176
	v_fma_f32 v140, v226, v225, v224
	v_mul_f32_e32 v144, 0x3db8aa3b, v140
	v_pk_mul_f32 v[128:129], v[128:129], v[144:145] op_sel_hi:[1,0]
	v_pk_mul_f32 v[124:125], v[124:125], v[144:145] op_sel_hi:[1,0]
	v_pk_mul_f32 v[140:141], v[126:127], v[144:145] op_sel_hi:[1,0]
	v_pk_mul_f32 v[126:127], v[122:123], v[144:145] op_sel_hi:[1,0]
	v_pk_mul_f32 v[120:121], v[120:121], v[144:145] op_sel_hi:[1,0]
	v_pk_mul_f32 v[122:123], v[118:119], v[144:145] op_sel_hi:[1,0]
	v_pk_mul_f32 v[116:117], v[116:117], v[144:145] op_sel_hi:[1,0]
	v_pk_mul_f32 v[118:119], v[114:115], v[144:145] op_sel_hi:[1,0]
	v_max_f32_e32 v114, v128, v129
	v_max_f32_e32 v115, v124, v125
	v_max_f32_e32 v144, v120, v121
	v_max_f32_e32 v146, v116, v117
	v_max3_f32 v114, v140, v141, v114
	v_max3_f32 v115, v126, v127, v115
	v_max3_f32 v144, v122, v123, v144
	v_max3_f32 v114, v114, s89, v115
	v_max3_f32 v115, v118, v119, v146
	v_max3_f32 v114, v114, v144, v115
	ds_bpermute_b32 v144, v177, v114
	v_xor_b32_e32 v115, 0x80, v145
	s_waitcnt lgkmcnt(0)
	v_max_f32_e32 v144, v144, v144
	v_max_f32_e32 v144, v114, v144
	ds_bpermute_b32 v145, v115, v144
	v_add_u32_e32 v114, s60, v160
	v_lshl_add_u32 v163, v114, 4, s68
	s_and_saveexec_b64 s[6:7], s[4:5]
	s_cbranch_execz .LBB0_2153
	s_waitcnt lgkmcnt(0)
	v_max_f32_e32 v145, v145, v145
	v_max_f32_e32 v144, v144, v144
	v_max_f32_e32 v144, v144, v145
	ds_write_b32 v163, v144
.LBB0_2153:
	s_or_b64 exec, exec, s[6:7]
	s_waitcnt lgkmcnt(0)
	global_load_dwordx4 v[144:147], v[142:143], off offset:1024
	global_load_dwordx4 v[148:151], v[142:143], off offset:1040
	global_load_dwordx4 v[152:155], v[142:143], off offset:1056
	global_load_dwordx4 v[156:159], v[142:143], off offset:1072
	s_waitcnt vmcnt(2)
	v_pk_add_f32 v[146:147], v[146:147], v[150:151]
	v_pk_add_f32 v[144:145], v[144:145], v[148:149]
	s_waitcnt vmcnt(0)
	v_pk_add_f32 v[148:149], v[154:155], v[158:159]
	v_pk_add_f32 v[150:151], v[152:153], v[156:157]
	v_pk_add_f32 v[146:147], v[146:147], v[148:149]
	v_pk_add_f32 v[144:145], v[144:145], v[150:151]
	s_nop 0
	v_pk_mov_b32 v[148:149], v[144:145], v[146:147] op_sel:[1,0]
	v_mov_b32_e32 v145, v147
	v_pk_add_f32 v[144:145], v[148:149], v[144:145]
	s_nop 0
	v_add_f32_e32 v144, v144, v145
	v_fmamk_f32 v144, v144, 0x3a800000, v212
	v_rsq_f32_e32 v224, v144
	s_nop 0
	v_mul_f32_e32 v225, v144, v224
	v_fma_f32 v225, -v225, v224, 1.0
	v_mul_f32_e32 v226, 0.5, v224
	s_nop 0
	v_fma_f32 v144, v226, v225, v224
	v_mul_f32_e32 v144, 0x3db8aa3b, v144
	v_pk_mul_f32 v[112:113], v[112:113], v[144:145] op_sel_hi:[1,0]
	v_pk_mul_f32 v[108:109], v[108:109], v[144:145] op_sel_hi:[1,0]
	v_pk_mul_f32 v[110:111], v[110:111], v[144:145] op_sel_hi:[1,0]
	v_pk_mul_f32 v[106:107], v[106:107], v[144:145] op_sel_hi:[1,0]
	v_pk_mul_f32 v[104:105], v[104:105], v[144:145] op_sel_hi:[1,0]
	v_pk_mul_f32 v[102:103], v[102:103], v[144:145] op_sel_hi:[1,0]
	v_pk_mul_f32 v[100:101], v[100:101], v[144:145] op_sel_hi:[1,0]
	v_pk_mul_f32 v[98:99], v[98:99], v[144:145] op_sel_hi:[1,0]
	v_max_f32_e32 v144, v112, v113
	v_max_f32_e32 v145, v108, v109
	v_max_f32_e32 v146, v104, v105
	v_max_f32_e32 v147, v100, v101
	v_max3_f32 v144, v110, v111, v144
	v_max3_f32 v145, v106, v107, v145
	v_max3_f32 v146, v102, v103, v146
	v_max3_f32 v144, v144, s89, v145
	v_max3_f32 v145, v98, v99, v147
	v_max3_f32 v144, v144, v146, v145
	ds_bpermute_b32 v145, v177, v144
	s_waitcnt lgkmcnt(0)
	v_max_f32_e32 v145, v145, v145
	v_max_f32_e32 v144, v144, v145
	ds_bpermute_b32 v145, v115, v144
	s_and_saveexec_b64 s[6:7], s[4:5]
	s_cbranch_execz .LBB0_2155
	s_waitcnt lgkmcnt(0)
	v_max_f32_e32 v145, v145, v145
	v_max_f32_e32 v144, v144, v144
	v_max_f32_e32 v144, v144, v145
	ds_write_b32 v163, v144 offset:256
.LBB0_2155:
	s_or_b64 exec, exec, s[6:7]
	s_waitcnt lgkmcnt(0)
	global_load_dwordx4 v[144:147], v[142:143], off offset:2048
	global_load_dwordx4 v[148:151], v[142:143], off offset:2064
	global_load_dwordx4 v[152:155], v[142:143], off offset:2080
	global_load_dwordx4 v[156:159], v[142:143], off offset:2096
	s_waitcnt vmcnt(2)
	v_pk_add_f32 v[146:147], v[146:147], v[150:151]
	v_pk_add_f32 v[144:145], v[144:145], v[148:149]
	s_waitcnt vmcnt(0)
	v_pk_add_f32 v[148:149], v[154:155], v[158:159]
	v_pk_add_f32 v[150:151], v[152:153], v[156:157]
	v_pk_add_f32 v[146:147], v[146:147], v[148:149]
	v_pk_add_f32 v[144:145], v[144:145], v[150:151]
	s_nop 0
	v_pk_mov_b32 v[148:149], v[144:145], v[146:147] op_sel:[1,0]
	v_mov_b32_e32 v145, v147
	v_pk_add_f32 v[144:145], v[148:149], v[144:145]
	s_nop 0
	v_add_f32_e32 v144, v144, v145
	v_fmamk_f32 v144, v144, 0x3a800000, v212
	v_rsq_f32_e32 v224, v144
	s_nop 0
	v_mul_f32_e32 v225, v144, v224
	v_fma_f32 v225, -v225, v224, 1.0
	v_mul_f32_e32 v226, 0.5, v224
	s_nop 0
	v_fma_f32 v144, v226, v225, v224
	v_mul_f32_e32 v144, 0x3db8aa3b, v144
	v_pk_mul_f32 v[96:97], v[96:97], v[144:145] op_sel_hi:[1,0]
	v_pk_mul_f32 v[92:93], v[92:93], v[144:145] op_sel_hi:[1,0]
	v_pk_mul_f32 v[94:95], v[94:95], v[144:145] op_sel_hi:[1,0]
	v_pk_mul_f32 v[90:91], v[90:91], v[144:145] op_sel_hi:[1,0]
	v_pk_mul_f32 v[88:89], v[88:89], v[144:145] op_sel_hi:[1,0]
	v_pk_mul_f32 v[86:87], v[86:87], v[144:145] op_sel_hi:[1,0]
	v_pk_mul_f32 v[84:85], v[84:85], v[144:145] op_sel_hi:[1,0]
	v_pk_mul_f32 v[82:83], v[82:83], v[144:145] op_sel_hi:[1,0]
	v_max_f32_e32 v144, v96, v97
	v_max_f32_e32 v145, v92, v93
	v_max_f32_e32 v146, v88, v89
	v_max_f32_e32 v147, v84, v85
	v_max3_f32 v144, v94, v95, v144
	v_max3_f32 v145, v90, v91, v145
	v_max3_f32 v146, v86, v87, v146
	v_max3_f32 v144, v144, s89, v145
	v_max3_f32 v145, v82, v83, v147
	v_max3_f32 v144, v144, v146, v145
	ds_bpermute_b32 v145, v177, v144
	s_waitcnt lgkmcnt(0)
	v_max_f32_e32 v145, v145, v145
	v_max_f32_e32 v144, v144, v145
	ds_bpermute_b32 v145, v115, v144
	s_and_saveexec_b64 s[6:7], s[4:5]
	s_cbranch_execz .LBB0_2157
	s_waitcnt lgkmcnt(0)
	v_max_f32_e32 v145, v145, v145
	v_max_f32_e32 v144, v144, v144
	v_max_f32_e32 v144, v144, v145
	ds_write_b32 v163, v144 offset:512
.LBB0_2157:
	s_or_b64 exec, exec, s[6:7]
	s_waitcnt lgkmcnt(0)
	global_load_dwordx4 v[144:147], v[142:143], off offset:3072
	global_load_dwordx4 v[148:151], v[142:143], off offset:3088
	global_load_dwordx4 v[152:155], v[142:143], off offset:3104
	global_load_dwordx4 v[156:159], v[142:143], off offset:3120
	s_waitcnt vmcnt(2)
	v_pk_add_f32 v[146:147], v[146:147], v[150:151]
	v_pk_add_f32 v[144:145], v[144:145], v[148:149]
	s_waitcnt vmcnt(0)
	v_pk_add_f32 v[148:149], v[154:155], v[158:159]
	v_pk_add_f32 v[150:151], v[152:153], v[156:157]
	v_pk_add_f32 v[146:147], v[146:147], v[148:149]
	v_pk_add_f32 v[144:145], v[144:145], v[150:151]
	s_nop 0
	v_pk_mov_b32 v[148:149], v[144:145], v[146:147] op_sel:[1,0]
	v_mov_b32_e32 v145, v147
	v_pk_add_f32 v[144:145], v[148:149], v[144:145]
	s_nop 0
	v_add_f32_e32 v144, v144, v145
	v_fmamk_f32 v144, v144, 0x3a800000, v212
	v_rsq_f32_e32 v224, v144
	s_nop 0
	v_mul_f32_e32 v225, v144, v224
	v_fma_f32 v225, -v225, v224, 1.0
	v_mul_f32_e32 v226, 0.5, v224
	s_nop 0
	v_fma_f32 v144, v226, v225, v224
	v_mul_f32_e32 v144, 0x3db8aa3b, v144
	v_pk_mul_f32 v[80:81], v[80:81], v[144:145] op_sel_hi:[1,0]
	v_pk_mul_f32 v[76:77], v[76:77], v[144:145] op_sel_hi:[1,0]
	v_pk_mul_f32 v[78:79], v[78:79], v[144:145] op_sel_hi:[1,0]
	v_pk_mul_f32 v[74:75], v[74:75], v[144:145] op_sel_hi:[1,0]
	v_pk_mul_f32 v[72:73], v[72:73], v[144:145] op_sel_hi:[1,0]
	v_pk_mul_f32 v[70:71], v[70:71], v[144:145] op_sel_hi:[1,0]
	v_pk_mul_f32 v[68:69], v[68:69], v[144:145] op_sel_hi:[1,0]
	v_pk_mul_f32 v[66:67], v[66:67], v[144:145] op_sel_hi:[1,0]
	v_max_f32_e32 v144, v80, v81
	v_max_f32_e32 v145, v76, v77
	v_max_f32_e32 v146, v72, v73
	v_max_f32_e32 v147, v68, v69
	v_max3_f32 v144, v78, v79, v144
	v_max3_f32 v145, v74, v75, v145
	v_max3_f32 v146, v70, v71, v146
	v_max3_f32 v144, v144, s89, v145
	v_max3_f32 v145, v66, v67, v147
	v_max3_f32 v144, v144, v146, v145
	ds_bpermute_b32 v145, v177, v144
	s_waitcnt lgkmcnt(0)
	v_max_f32_e32 v145, v145, v145
	v_max_f32_e32 v144, v144, v145
	ds_bpermute_b32 v145, v115, v144
	s_and_saveexec_b64 s[6:7], s[4:5]
	s_cbranch_execz .LBB0_2159
	s_waitcnt lgkmcnt(0)
	v_max_f32_e32 v145, v145, v145
	v_max_f32_e32 v144, v144, v144
	v_max_f32_e32 v144, v144, v145
	ds_write_b32 v163, v144 offset:768
.LBB0_2159:
	s_or_b64 exec, exec, s[6:7]
	v_add_co_u32_e32 v144, vcc, 0x2000, v142
	v_lshl_add_u64 v[156:157], v[142:143], 0, s[28:29]
	s_waitcnt lgkmcnt(0)
	v_addc_co_u32_e32 v145, vcc, 0, v143, vcc
	global_load_dwordx4 v[144:147], v[144:145], off
	s_nop 0
	global_load_dwordx4 v[148:151], v[156:157], off offset:16
	global_load_dwordx4 v[152:155], v[156:157], off offset:32
	s_nop 0
	global_load_dwordx4 v[156:159], v[156:157], off offset:48
	s_waitcnt vmcnt(2)
	v_pk_add_f32 v[146:147], v[146:147], v[150:151]
	v_pk_add_f32 v[144:145], v[144:145], v[148:149]
	s_waitcnt vmcnt(0)
	v_pk_add_f32 v[148:149], v[154:155], v[158:159]
	v_pk_add_f32 v[150:151], v[152:153], v[156:157]
	v_pk_add_f32 v[146:147], v[146:147], v[148:149]
	v_pk_add_f32 v[144:145], v[144:145], v[150:151]
	s_nop 0
	v_pk_mov_b32 v[148:149], v[144:145], v[146:147] op_sel:[1,0]
	v_mov_b32_e32 v145, v147
	v_pk_add_f32 v[144:145], v[148:149], v[144:145]
	s_nop 0
	v_add_f32_e32 v144, v144, v145
	v_fmamk_f32 v144, v144, 0x3a800000, v212
	v_rsq_f32_e32 v224, v144
	s_nop 0
	v_mul_f32_e32 v225, v144, v224
	v_fma_f32 v225, -v225, v224, 1.0
	v_mul_f32_e32 v226, 0.5, v224
	s_nop 0
	v_fma_f32 v144, v226, v225, v224
	v_mul_f32_e32 v146, 0x3db8aa3b, v144
	v_pk_mul_f32 v[64:65], v[64:65], v[146:147] op_sel_hi:[1,0]
	v_pk_mul_f32 v[60:61], v[60:61], v[146:147] op_sel_hi:[1,0]
	v_pk_mul_f32 v[144:145], v[62:63], v[146:147] op_sel_hi:[1,0]
	v_pk_mul_f32 v[62:63], v[58:59], v[146:147] op_sel_hi:[1,0]
	v_pk_mul_f32 v[56:57], v[56:57], v[146:147] op_sel_hi:[1,0]
	v_pk_mul_f32 v[58:59], v[54:55], v[146:147] op_sel_hi:[1,0]
	v_pk_mul_f32 v[52:53], v[52:53], v[146:147] op_sel_hi:[1,0]
	v_pk_mul_f32 v[54:55], v[50:51], v[146:147] op_sel_hi:[1,0]
	v_max_f32_e32 v50, v64, v65
	v_max_f32_e32 v51, v60, v61
	v_max_f32_e32 v146, v56, v57
	v_max_f32_e32 v147, v52, v53
	v_max3_f32 v50, v144, v145, v50
	v_max3_f32 v51, v62, v63, v51
	v_max3_f32 v146, v58, v59, v146
	v_max3_f32 v50, v50, s89, v51
	v_max3_f32 v51, v54, v55, v147
	v_max3_f32 v50, v50, v146, v51
	ds_bpermute_b32 v51, v177, v50
	s_waitcnt lgkmcnt(0)
	v_max_f32_e32 v51, v51, v51
	v_max_f32_e32 v51, v50, v51
	ds_bpermute_b32 v146, v115, v51
	v_add_u32_e32 v50, 0x80, v114
	s_and_saveexec_b64 s[6:7], s[4:5]
	s_cbranch_execz .LBB0_2161
	s_waitcnt lgkmcnt(0)
	v_max_f32_e32 v146, v146, v146
	v_max_f32_e32 v51, v51, v51
	v_lshl_add_u32 v147, v50, 4, s68
	v_max_f32_e32 v51, v51, v146
	ds_write_b32 v147, v51
.LBB0_2161:
	s_or_b64 exec, exec, s[6:7]
	s_mov_b64 s[6:7], 0x2400
	s_waitcnt lgkmcnt(0)
	v_add_co_u32_e32 v146, vcc, 0x2000, v142
	v_lshl_add_u64 v[158:159], v[142:143], 0, s[6:7]
	s_nop 0
	v_addc_co_u32_e32 v147, vcc, 0, v143, vcc
	global_load_dwordx4 v[146:149], v[146:147], off offset:1024
	s_nop 0
	global_load_dwordx4 v[150:153], v[158:159], off offset:16
	global_load_dwordx4 v[154:157], v[158:159], off offset:32
	s_nop 0
	global_load_dwordx4 v[158:161], v[158:159], off offset:48
	s_waitcnt vmcnt(2)
	v_pk_add_f32 v[148:149], v[148:149], v[152:153]
	v_pk_add_f32 v[146:147], v[146:147], v[150:151]
	s_waitcnt vmcnt(0)
	v_pk_add_f32 v[150:151], v[156:157], v[160:161]
	v_pk_add_f32 v[152:153], v[154:155], v[158:159]
	v_pk_add_f32 v[148:149], v[148:149], v[150:151]
	v_pk_add_f32 v[146:147], v[146:147], v[152:153]
	s_nop 0
	v_pk_mov_b32 v[150:151], v[146:147], v[148:149] op_sel:[1,0]
	v_mov_b32_e32 v147, v149
	v_pk_add_f32 v[146:147], v[150:151], v[146:147]
	s_nop 0
	v_add_f32_e32 v51, v146, v147
	v_fmamk_f32 v51, v51, 0x3a800000, v212
	v_rsq_f32_e32 v224, v51
	s_nop 0
	v_mul_f32_e32 v225, v51, v224
	v_fma_f32 v225, -v225, v224, 1.0
	v_mul_f32_e32 v226, 0.5, v224
	s_nop 0
	v_fma_f32 v51, v226, v225, v224
	v_mul_f32_e32 v154, 0x3db8aa3b, v51
	v_pk_mul_f32 v[150:151], v[48:49], v[154:155] op_sel_hi:[1,0]
	v_pk_mul_f32 v[48:49], v[44:45], v[154:155] op_sel_hi:[1,0]
	v_pk_mul_f32 v[152:153], v[46:47], v[154:155] op_sel_hi:[1,0]
	v_pk_mul_f32 v[42:43], v[42:43], v[154:155] op_sel_hi:[1,0]
	v_pk_mul_f32 v[146:147], v[40:41], v[154:155] op_sel_hi:[1,0]
	v_pk_mul_f32 v[46:47], v[36:37], v[154:155] op_sel_hi:[1,0]
	v_pk_mul_f32 v[40:41], v[34:35], v[154:155] op_sel_hi:[1,0]
	v_max_f32_e32 v34, v150, v151
	v_max_f32_e32 v35, v48, v49
	v_pk_mul_f32 v[148:149], v[38:39], v[154:155] op_sel_hi:[1,0]
	v_max_f32_e32 v36, v146, v147
	v_max_f32_e32 v37, v46, v47
	v_max3_f32 v34, v152, v153, v34
	v_max3_f32 v35, v42, v43, v35
	v_max3_f32 v36, v148, v149, v36
	v_max3_f32 v34, v34, s89, v35
	v_max3_f32 v35, v40, v41, v37
	v_max3_f32 v34, v34, v36, v35
	ds_bpermute_b32 v35, v177, v34
	s_waitcnt lgkmcnt(0)
	v_max_f32_e32 v35, v35, v35
	v_max_f32_e32 v34, v34, v35
	ds_bpermute_b32 v35, v115, v34
	s_and_saveexec_b64 s[6:7], s[4:5]
	s_cbranch_execz .LBB0_2163
	s_waitcnt lgkmcnt(0)
	v_max_f32_e32 v35, v35, v35
	v_max_f32_e32 v34, v34, v34
	v_max_f32_e32 v34, v34, v35
	ds_write_b32 v163, v34 offset:2304
.LBB0_2163:
	s_or_b64 exec, exec, s[6:7]
	v_add_co_u32_e32 v34, vcc, 0x2000, v142
	s_mov_b64 s[6:7], 0x2800
	s_waitcnt lgkmcnt(0)
	v_addc_co_u32_e32 v35, vcc, 0, v143, vcc
	v_lshl_add_u64 v[38:39], v[142:143], 0, s[6:7]
	global_load_dwordx4 v[34:37], v[34:35], off offset:2048
	s_nop 0
	global_load_dwordx4 v[154:157], v[38:39], off offset:16
	global_load_dwordx4 v[158:161], v[38:39], off offset:32
	global_load_dwordx4 v[164:167], v[38:39], off offset:48
	s_waitcnt vmcnt(2)
	v_pk_add_f32 v[36:37], v[36:37], v[156:157]
	v_pk_add_f32 v[34:35], v[34:35], v[154:155]
	s_waitcnt vmcnt(0)
	v_pk_add_f32 v[38:39], v[160:161], v[166:167]
	v_pk_add_f32 v[44:45], v[158:159], v[164:165]
	v_pk_add_f32 v[36:37], v[36:37], v[38:39]
	v_pk_add_f32 v[34:35], v[34:35], v[44:45]
	s_nop 0
	v_pk_mov_b32 v[38:39], v[34:35], v[36:37] op_sel:[1,0]
	v_mov_b32_e32 v35, v37
	v_pk_add_f32 v[34:35], v[38:39], v[34:35]
	s_nop 0
	v_add_f32_e32 v34, v34, v35
	v_fmamk_f32 v34, v34, 0x3a800000, v212
	v_rsq_f32_e32 v224, v34
	s_nop 0
	v_mul_f32_e32 v225, v34, v224
	v_fma_f32 v225, -v225, v224, 1.0
	v_mul_f32_e32 v226, 0.5, v224
	s_nop 0
	v_fma_f32 v34, v226, v225, v224
	v_mul_f32_e32 v34, 0x3db8aa3b, v34
	v_pk_mul_f32 v[158:159], v[32:33], v[34:35] op_sel_hi:[1,0]
	v_pk_mul_f32 v[32:33], v[28:29], v[34:35] op_sel_hi:[1,0]
	v_pk_mul_f32 v[160:161], v[30:31], v[34:35] op_sel_hi:[1,0]
	v_pk_mul_f32 v[26:27], v[26:27], v[34:35] op_sel_hi:[1,0]
	v_pk_mul_f32 v[154:155], v[24:25], v[34:35] op_sel_hi:[1,0]
	v_pk_mul_f32 v[30:31], v[20:21], v[34:35] op_sel_hi:[1,0]
	v_pk_mul_f32 v[24:25], v[18:19], v[34:35] op_sel_hi:[1,0]
	v_max_f32_e32 v18, v158, v159
	v_max_f32_e32 v19, v32, v33
	v_pk_mul_f32 v[156:157], v[22:23], v[34:35] op_sel_hi:[1,0]
	v_max_f32_e32 v20, v154, v155
	v_max_f32_e32 v21, v30, v31
	v_max3_f32 v18, v160, v161, v18
	v_max3_f32 v19, v26, v27, v19
	v_max3_f32 v20, v156, v157, v20
	v_max3_f32 v18, v18, s89, v19
	v_max3_f32 v19, v24, v25, v21
	v_max3_f32 v18, v18, v20, v19
	ds_bpermute_b32 v19, v177, v18
	s_waitcnt lgkmcnt(0)
	v_max_f32_e32 v19, v19, v19
	v_max_f32_e32 v18, v18, v19
	ds_bpermute_b32 v19, v115, v18
	s_and_saveexec_b64 s[6:7], s[4:5]
	s_cbranch_execz .LBB0_2165
	s_waitcnt lgkmcnt(0)
	v_max_f32_e32 v19, v19, v19
	v_max_f32_e32 v18, v18, v18
	v_max_f32_e32 v18, v18, v19
	ds_write_b32 v163, v18 offset:2560
.LBB0_2165:
	s_or_b64 exec, exec, s[6:7]
	v_add_co_u32_e32 v18, vcc, 0x2000, v142
	s_mov_b64 s[6:7], 0x2c00
	s_waitcnt lgkmcnt(0)
	v_addc_co_u32_e32 v19, vcc, 0, v143, vcc
	v_lshl_add_u64 v[22:23], v[142:143], 0, s[6:7]
	global_load_dwordx4 v[18:21], v[18:19], off offset:3072
	s_nop 0
	global_load_dwordx4 v[34:37], v[22:23], off offset:16
	global_load_dwordx4 v[164:167], v[22:23], off offset:32
	global_load_dwordx4 v[168:171], v[22:23], off offset:48
	s_waitcnt vmcnt(2)
	v_pk_add_f32 v[20:21], v[20:21], v[36:37]
	v_pk_add_f32 v[18:19], v[18:19], v[34:35]
	s_waitcnt vmcnt(0)
	v_pk_add_f32 v[22:23], v[166:167], v[170:171]
	v_pk_add_f32 v[28:29], v[164:165], v[168:169]
	v_pk_add_f32 v[20:21], v[20:21], v[22:23]
	v_pk_add_f32 v[18:19], v[18:19], v[28:29]
	s_nop 0
	v_pk_mov_b32 v[22:23], v[18:19], v[20:21] op_sel:[1,0]
	v_mov_b32_e32 v19, v21
	v_pk_add_f32 v[18:19], v[22:23], v[18:19]
	s_nop 0
	v_add_f32_e32 v18, v18, v19
	v_fmamk_f32 v18, v18, 0x3a800000, v212
	v_rsq_f32_e32 v224, v18
	s_nop 0
	v_mul_f32_e32 v225, v18, v224
	v_fma_f32 v225, -v225, v224, 1.0
	v_mul_f32_e32 v226, 0.5, v224
	s_nop 0
	v_fma_f32 v18, v226, v225, v224
	v_mul_f32_e32 v18, 0x3db8aa3b, v18
	v_pk_mul_f32 v[168:169], v[16:17], v[18:19] op_sel_hi:[1,0]
	v_pk_mul_f32 v[16:17], v[12:13], v[18:19] op_sel_hi:[1,0]
	v_pk_mul_f32 v[170:171], v[14:15], v[18:19] op_sel_hi:[1,0]
	v_pk_mul_f32 v[10:11], v[10:11], v[18:19] op_sel_hi:[1,0]
	v_pk_mul_f32 v[164:165], v[8:9], v[18:19] op_sel_hi:[1,0]
	v_pk_mul_f32 v[14:15], v[4:5], v[18:19] op_sel_hi:[1,0]
	v_pk_mul_f32 v[8:9], v[2:3], v[18:19] op_sel_hi:[1,0]
	v_max_f32_e32 v2, v168, v169
	v_max_f32_e32 v3, v16, v17
	v_pk_mul_f32 v[166:167], v[6:7], v[18:19] op_sel_hi:[1,0]
	v_max_f32_e32 v4, v164, v165
	v_max_f32_e32 v5, v14, v15
	v_max3_f32 v2, v170, v171, v2
	v_max3_f32 v3, v10, v11, v3
	v_max3_f32 v4, v166, v167, v4
	v_max3_f32 v2, v2, s89, v3
	v_max3_f32 v3, v8, v9, v5
	v_max3_f32 v2, v2, v4, v3
	ds_bpermute_b32 v3, v177, v2
	s_waitcnt lgkmcnt(0)
	v_max_f32_e32 v3, v3, v3
	v_max_f32_e32 v2, v2, v3
	ds_bpermute_b32 v3, v115, v2
	s_and_saveexec_b64 s[6:7], s[4:5]
	s_cbranch_execz .LBB0_2167
	s_waitcnt lgkmcnt(0)
	v_max_f32_e32 v3, v3, v3
	v_max_f32_e32 v2, v2, v2
	v_max_f32_e32 v2, v2, v3
	ds_write_b32 v163, v2 offset:2816

.LBB0_2431:
	v_lshl_add_u32 v142, s67, 8, v146
	v_ashrrev_i32_e32 v143, 31, v142
	v_lshlrev_b64 v[140:141], 6, v[142:143]
	v_lshl_add_u64 v[140:141], s[18:19], 0, v[140:141]
	v_mbcnt_lo_u32_b32 v252, -1, 0
	v_mbcnt_hi_u32_b32 v252, -1, v252
	v_and_b32_e32 v252, 0x30, v252
	v_mov_b32_e32 v253, 0
	v_lshl_add_u64 v[248:249], v[140:141], 0, v[252:253]
	s_mov_b64 s[100:101], 0x2000
	v_lshl_add_u64 v[250:251], v[248:249], 0, s[100:101]
	global_load_dwordx4 v[216:219], v[248:249], off
	global_load_dwordx4 v[220:223], v[248:249], off offset:1024
	s_waitcnt vmcnt(1)
	v_add_f32_e32 v216, v216, v217
	v_add_f32_e32 v218, v218, v219
	v_add_f32_e32 v216, v216, v218
	v_mov_b32_e32 v252, v216
	s_nop 1
	v_permlane16_swap_b32_e32 v252, v216
	v_add_f32_e32 v216, v216, v252
	v_mov_b32_e32 v252, v216
	s_nop 1
	v_permlane32_swap_b32_e32 v252, v216
	v_add_f32_e32 v140, v216, v252
	v_fmamk_f32 v140, v140, 0x3a800000, v212
	v_rsq_f32_e32 v224, v140
	s_nop 0
	v_mul_f32_e32 v225, v140, v224
	v_fma_f32 v225, -v225, v224, 1.0
	v_mul_f32_e32 v226, 0.5, v224
	v_lshl_or_b32 v140, s6, 8, v148
	v_cmp_gt_i32_e64 s[4:5], 2.0, v140
	v_ashrrev_i32_e32 v141, 31, v140
	v_lshlrev_b64 v[150:151], 13, v[142:143]
	s_nop 0
	v_fma_f32 v144, v226, v225, v224
	v_pk_mul_f32 v[128:129], v[128:129], v[144:145] op_sel_hi:[1,0]
	v_pk_mul_f32 v[126:127], v[126:127], v[144:145] op_sel_hi:[1,0]
	v_pk_mul_f32 v[124:125], v[124:125], v[144:145] op_sel_hi:[1,0]
	v_pk_mul_f32 v[122:123], v[122:123], v[144:145] op_sel_hi:[1,0]
	v_max_f32_e32 v126, 0, v126
	v_max_f32_e32 v122, 0, v122
	v_max_f32_e32 v127, 0, v127
	v_max_f32_e32 v123, 0, v123
	v_max_f32_e32 v128, 0, v128
	v_max_f32_e32 v124, 0, v124
	v_max_f32_e32 v129, 0, v129
	v_max_f32_e32 v125, 0, v125
	v_mul_f32_e32 v126, v126, v126
	v_mul_f32_e32 v143, v122, v122
	v_mul_f32_e32 v122, v127, v127
	v_mul_f32_e32 v127, v123, v123
	v_mul_f32_e32 v123, v128, v128
	v_mul_f32_e32 v128, v124, v124
	v_mul_f32_e32 v124, v129, v129
	v_mul_f32_e32 v125, v125, v125
	v_cvt_pk_bf16_f32 v122, v126, v122
	v_cvt_pk_bf16_f32 v123, v123, v124
	v_cvt_pk_bf16_f32 v124, v143, v127
	v_lshl_add_u64 v[126:127], s[40:41], 0, v[150:151]
	v_cvt_pk_bf16_f32 v125, v128, v125
	s_and_saveexec_b64 s[6:7], s[4:5]
	s_cbranch_execz .LBB0_2433
	v_lshl_add_u64 v[128:129], v[140:141], 1, v[126:127]
	global_store_dwordx4 v[128:129], v[122:125], off nt

.LBB0_2435:
	s_or_b64 exec, exec, s[8:9]
	v_or_b32_e32 v144, 16, v142
	v_ashrrev_i32_e32 v145, 31, v144
	v_lshlrev_b64 v[114:115], 6, v[144:145]
	v_lshl_add_u64 v[126:127], s[18:19], 0, v[114:115]
	global_load_dwordx4 v[216:219], v[248:249], off offset:2048
	s_waitcnt vmcnt(3)
	v_add_f32_e32 v220, v220, v221
	v_add_f32_e32 v222, v222, v223
	v_add_f32_e32 v220, v220, v222
	v_mov_b32_e32 v252, v220
	s_nop 1
	v_permlane16_swap_b32_e32 v252, v220
	v_add_f32_e32 v220, v220, v252
	v_mov_b32_e32 v252, v220
	s_nop 1
	v_permlane32_swap_b32_e32 v252, v220
	v_add_f32_e32 v114, v220, v252
	v_fmamk_f32 v114, v114, 0x3a800000, v212
	v_rsq_f32_e32 v224, v114
	s_nop 0
	v_mul_f32_e32 v225, v114, v224
	v_fma_f32 v225, -v225, v224, 1.0
	v_mul_f32_e32 v226, 0.5, v224
	s_nop 0
	v_lshlrev_b64 v[116:117], 13, v[144:145]
	s_nop 0
	v_fma_f32 v114, v226, v225, v224
	v_pk_mul_f32 v[112:113], v[112:113], v[114:115] op_sel_hi:[1,0]
	v_pk_mul_f32 v[110:111], v[110:111], v[114:115] op_sel_hi:[1,0]
	v_pk_mul_f32 v[108:109], v[108:109], v[114:115] op_sel_hi:[1,0]
	v_pk_mul_f32 v[106:107], v[106:107], v[114:115] op_sel_hi:[1,0]
	v_max_f32_e32 v110, 0, v110
	v_max_f32_e32 v106, 0, v106
	v_max_f32_e32 v111, 0, v111
	v_max_f32_e32 v107, 0, v107
	v_max_f32_e32 v112, 0, v112
	v_max_f32_e32 v108, 0, v108
	v_max_f32_e32 v113, 0, v113
	v_max_f32_e32 v109, 0, v109
	v_mul_f32_e32 v110, v110, v110
	v_mul_f32_e32 v115, v106, v106
	v_mul_f32_e32 v106, v111, v111
	v_mul_f32_e32 v111, v107, v107
	v_mul_f32_e32 v107, v112, v112
	v_mul_f32_e32 v112, v108, v108
	v_mul_f32_e32 v108, v113, v113
	v_mul_f32_e32 v109, v109, v109
	v_cvt_pk_bf16_f32 v106, v110, v106
	v_cvt_pk_bf16_f32 v107, v107, v108
	v_cvt_pk_bf16_f32 v108, v115, v111
	v_lshl_add_u64 v[110:111], s[40:41], 0, v[116:117]
	v_cvt_pk_bf16_f32 v109, v112, v109
	s_and_saveexec_b64 s[8:9], s[4:5]
	s_cbranch_execz .LBB0_2437
	v_lshl_add_u64 v[112:113], v[140:141], 1, v[110:111]
	global_store_dwordx4 v[112:113], v[106:109], off nt

.LBB0_2439:
	s_or_b64 exec, exec, s[8:9]
	v_or_b32_e32 v114, 32, v142
	v_ashrrev_i32_e32 v115, 31, v114
	v_lshlrev_b64 v[98:99], 6, v[114:115]
	v_lshl_add_u64 v[110:111], s[18:19], 0, v[98:99]
	global_load_dwordx4 v[220:223], v[248:249], off offset:3072
	s_waitcnt vmcnt(3)
	v_add_f32_e32 v216, v216, v217
	v_add_f32_e32 v218, v218, v219
	v_add_f32_e32 v216, v216, v218
	v_mov_b32_e32 v252, v216
	s_nop 1
	v_permlane16_swap_b32_e32 v252, v216
	v_add_f32_e32 v216, v216, v252
	v_mov_b32_e32 v252, v216
	s_nop 1
	v_permlane32_swap_b32_e32 v252, v216
	v_add_f32_e32 v98, v216, v252
	v_fmamk_f32 v98, v98, 0x3a800000, v212
	v_rsq_f32_e32 v224, v98
	s_nop 0
	v_mul_f32_e32 v225, v98, v224
	v_fma_f32 v225, -v225, v224, 1.0
	v_mul_f32_e32 v226, 0.5, v224
	s_nop 0
	v_lshlrev_b64 v[100:101], 13, v[114:115]
	s_nop 0
	v_fma_f32 v98, v226, v225, v224
	v_pk_mul_f32 v[96:97], v[96:97], v[98:99] op_sel_hi:[1,0]
	v_pk_mul_f32 v[94:95], v[94:95], v[98:99] op_sel_hi:[1,0]
	v_pk_mul_f32 v[92:93], v[92:93], v[98:99] op_sel_hi:[1,0]
	v_pk_mul_f32 v[90:91], v[90:91], v[98:99] op_sel_hi:[1,0]
	v_max_f32_e32 v94, 0, v94
	v_max_f32_e32 v90, 0, v90
	v_max_f32_e32 v95, 0, v95
	v_max_f32_e32 v91, 0, v91
	v_max_f32_e32 v96, 0, v96
	v_max_f32_e32 v92, 0, v92
	v_max_f32_e32 v97, 0, v97
	v_max_f32_e32 v93, 0, v93
	v_mul_f32_e32 v94, v94, v94
	v_mul_f32_e32 v99, v90, v90
	v_mul_f32_e32 v90, v95, v95
	v_mul_f32_e32 v95, v91, v91
	v_mul_f32_e32 v91, v96, v96
	v_mul_f32_e32 v96, v92, v92
	v_mul_f32_e32 v92, v97, v97
	v_mul_f32_e32 v93, v93, v93
	v_cvt_pk_bf16_f32 v90, v94, v90
	v_cvt_pk_bf16_f32 v91, v91, v92
	v_cvt_pk_bf16_f32 v92, v99, v95
	v_lshl_add_u64 v[94:95], s[40:41], 0, v[100:101]
	v_cvt_pk_bf16_f32 v93, v96, v93
	s_and_saveexec_b64 s[8:9], s[4:5]
	s_cbranch_execz .LBB0_2441
	v_lshl_add_u64 v[96:97], v[140:141], 1, v[94:95]
	global_store_dwordx4 v[96:97], v[90:93], off nt

.LBB0_2443:
	s_or_b64 exec, exec, s[8:9]
	v_or_b32_e32 v98, 48, v142
	v_ashrrev_i32_e32 v99, 31, v98
	v_lshlrev_b64 v[82:83], 6, v[98:99]
	v_lshl_add_u64 v[94:95], s[18:19], 0, v[82:83]
	global_load_dwordx4 v[216:219], v[250:251], off
	s_waitcnt vmcnt(3)
	v_add_f32_e32 v220, v220, v221
	v_add_f32_e32 v222, v222, v223
	v_add_f32_e32 v220, v220, v222
	v_mov_b32_e32 v252, v220
	s_nop 1
	v_permlane16_swap_b32_e32 v252, v220
	v_add_f32_e32 v220, v220, v252
	v_mov_b32_e32 v252, v220
	s_nop 1
	v_permlane32_swap_b32_e32 v252, v220
	v_add_f32_e32 v82, v220, v252
	v_fmamk_f32 v82, v82, 0x3a800000, v212
	v_rsq_f32_e32 v224, v82
	s_nop 0
	v_mul_f32_e32 v225, v82, v224
	v_fma_f32 v225, -v225, v224, 1.0
	v_mul_f32_e32 v226, 0.5, v224
	s_nop 0
	v_lshlrev_b64 v[84:85], 13, v[98:99]
	s_nop 0
	v_fma_f32 v82, v226, v225, v224
	v_pk_mul_f32 v[80:81], v[80:81], v[82:83] op_sel_hi:[1,0]
	v_pk_mul_f32 v[78:79], v[78:79], v[82:83] op_sel_hi:[1,0]
	v_pk_mul_f32 v[76:77], v[76:77], v[82:83] op_sel_hi:[1,0]
	v_pk_mul_f32 v[74:75], v[74:75], v[82:83] op_sel_hi:[1,0]
	v_max_f32_e32 v78, 0, v78
	v_max_f32_e32 v74, 0, v74
	v_max_f32_e32 v79, 0, v79
	v_max_f32_e32 v75, 0, v75
	v_max_f32_e32 v80, 0, v80
	v_max_f32_e32 v76, 0, v76
	v_max_f32_e32 v81, 0, v81
	v_max_f32_e32 v77, 0, v77
	v_mul_f32_e32 v78, v78, v78
	v_mul_f32_e32 v83, v74, v74
	v_mul_f32_e32 v74, v79, v79
	v_mul_f32_e32 v79, v75, v75
	v_mul_f32_e32 v75, v80, v80
	v_mul_f32_e32 v80, v76, v76
	v_mul_f32_e32 v76, v81, v81
	v_mul_f32_e32 v77, v77, v77
	v_cvt_pk_bf16_f32 v74, v78, v74
	v_cvt_pk_bf16_f32 v75, v75, v76
	v_cvt_pk_bf16_f32 v76, v83, v79
	v_lshl_add_u64 v[78:79], s[40:41], 0, v[84:85]
	v_cvt_pk_bf16_f32 v77, v80, v77
	s_and_saveexec_b64 s[8:9], s[4:5]
	s_cbranch_execz .LBB0_2445
	v_lshl_add_u64 v[80:81], v[140:141], 1, v[78:79]
	global_store_dwordx4 v[80:81], v[74:77], off nt

.LBB0_2447:
	s_or_b64 exec, exec, s[8:9]
	v_add_u32_e32 v82, 0x80, v142
	v_ashrrev_i32_e32 v83, 31, v82
	v_lshlrev_b64 v[66:67], 6, v[82:83]
	v_lshl_add_u64 v[78:79], s[18:19], 0, v[66:67]
	global_load_dwordx4 v[220:223], v[250:251], off offset:1024
	s_waitcnt vmcnt(3)
	v_add_f32_e32 v216, v216, v217
	v_add_f32_e32 v218, v218, v219
	v_add_f32_e32 v216, v216, v218
	v_mov_b32_e32 v252, v216
	s_nop 1
	v_permlane16_swap_b32_e32 v252, v216
	v_add_f32_e32 v216, v216, v252
	v_mov_b32_e32 v252, v216
	s_nop 1
	v_permlane32_swap_b32_e32 v252, v216
	v_add_f32_e32 v66, v216, v252
	v_fmamk_f32 v66, v66, 0x3a800000, v212
	v_rsq_f32_e32 v224, v66
	s_nop 0
	v_mul_f32_e32 v225, v66, v224
	v_fma_f32 v225, -v225, v224, 1.0
	v_mul_f32_e32 v226, 0.5, v224
	s_nop 0
	v_lshlrev_b64 v[68:69], 13, v[82:83]
	s_nop 0
	v_fma_f32 v66, v226, v225, v224
	v_pk_mul_f32 v[64:65], v[64:65], v[66:67] op_sel_hi:[1,0]
	v_pk_mul_f32 v[62:63], v[62:63], v[66:67] op_sel_hi:[1,0]
	v_pk_mul_f32 v[60:61], v[60:61], v[66:67] op_sel_hi:[1,0]
	v_pk_mul_f32 v[58:59], v[58:59], v[66:67] op_sel_hi:[1,0]
	v_max_f32_e32 v62, 0, v62
	v_max_f32_e32 v58, 0, v58
	v_max_f32_e32 v63, 0, v63
	v_max_f32_e32 v59, 0, v59
	v_max_f32_e32 v64, 0, v64
	v_max_f32_e32 v60, 0, v60
	v_max_f32_e32 v65, 0, v65
	v_max_f32_e32 v61, 0, v61
	v_mul_f32_e32 v62, v62, v62
	v_mul_f32_e32 v67, v58, v58
	v_mul_f32_e32 v58, v63, v63
	v_mul_f32_e32 v63, v59, v59
	v_mul_f32_e32 v59, v64, v64
	v_mul_f32_e32 v64, v60, v60
	v_mul_f32_e32 v60, v65, v65
	v_mul_f32_e32 v61, v61, v61
	v_cvt_pk_bf16_f32 v58, v62, v58
	v_cvt_pk_bf16_f32 v59, v59, v60
	v_cvt_pk_bf16_f32 v60, v67, v63
	v_lshl_add_u64 v[62:63], s[40:41], 0, v[68:69]
	v_cvt_pk_bf16_f32 v61, v64, v61
	s_and_saveexec_b64 s[8:9], s[4:5]
	s_cbranch_execz .LBB0_2449
	v_lshl_add_u64 v[64:65], v[140:141], 1, v[62:63]
	global_store_dwordx4 v[64:65], v[58:61], off nt

.LBB0_2451:
	s_or_b64 exec, exec, s[8:9]
	v_add_u32_e32 v66, 0x90, v142
	v_ashrrev_i32_e32 v67, 31, v66
	v_lshlrev_b64 v[50:51], 6, v[66:67]
	v_lshl_add_u64 v[62:63], s[18:19], 0, v[50:51]
	global_load_dwordx4 v[216:219], v[250:251], off offset:2048
	s_waitcnt vmcnt(3)
	v_add_f32_e32 v220, v220, v221
	v_add_f32_e32 v222, v222, v223
	v_add_f32_e32 v220, v220, v222
	v_mov_b32_e32 v252, v220
	s_nop 1
	v_permlane16_swap_b32_e32 v252, v220
	v_add_f32_e32 v220, v220, v252
	v_mov_b32_e32 v252, v220
	s_nop 1
	v_permlane32_swap_b32_e32 v252, v220
	v_add_f32_e32 v50, v220, v252
	v_fmamk_f32 v50, v50, 0x3a800000, v212
	v_rsq_f32_e32 v224, v50
	s_nop 0
	v_mul_f32_e32 v225, v50, v224
	v_fma_f32 v225, -v225, v224, 1.0
	v_mul_f32_e32 v226, 0.5, v224
	s_nop 0
	v_lshlrev_b64 v[52:53], 13, v[66:67]
	s_nop 0
	v_fma_f32 v50, v226, v225, v224
	v_pk_mul_f32 v[48:49], v[48:49], v[50:51] op_sel_hi:[1,0]
	v_pk_mul_f32 v[46:47], v[46:47], v[50:51] op_sel_hi:[1,0]
	v_pk_mul_f32 v[44:45], v[44:45], v[50:51] op_sel_hi:[1,0]
	v_pk_mul_f32 v[42:43], v[42:43], v[50:51] op_sel_hi:[1,0]
	v_max_f32_e32 v46, 0, v46
	v_max_f32_e32 v42, 0, v42
	v_max_f32_e32 v47, 0, v47
	v_max_f32_e32 v43, 0, v43
	v_max_f32_e32 v48, 0, v48
	v_max_f32_e32 v44, 0, v44
	v_max_f32_e32 v49, 0, v49
	v_max_f32_e32 v45, 0, v45
	v_mul_f32_e32 v46, v46, v46
	v_mul_f32_e32 v51, v42, v42
	v_mul_f32_e32 v42, v47, v47
	v_mul_f32_e32 v47, v43, v43
	v_mul_f32_e32 v43, v48, v48
	v_mul_f32_e32 v48, v44, v44
	v_mul_f32_e32 v44, v49, v49
	v_mul_f32_e32 v45, v45, v45
	v_cvt_pk_bf16_f32 v42, v46, v42
	v_cvt_pk_bf16_f32 v43, v43, v44
	v_cvt_pk_bf16_f32 v44, v51, v47
	v_lshl_add_u64 v[46:47], s[40:41], 0, v[52:53]
	v_cvt_pk_bf16_f32 v45, v48, v45
	s_and_saveexec_b64 s[8:9], s[4:5]
	s_cbranch_execz .LBB0_2453
	v_lshl_add_u64 v[48:49], v[140:141], 1, v[46:47]
	global_store_dwordx4 v[48:49], v[42:45], off nt

.LBB0_2455:
	s_or_b64 exec, exec, s[8:9]
	v_add_u32_e32 v50, 0xa0, v142
	v_ashrrev_i32_e32 v51, 31, v50
	v_lshlrev_b64 v[34:35], 6, v[50:51]
	v_lshl_add_u64 v[46:47], s[18:19], 0, v[34:35]
	global_load_dwordx4 v[220:223], v[250:251], off offset:3072
	s_waitcnt vmcnt(3)
	v_add_f32_e32 v216, v216, v217
	v_add_f32_e32 v218, v218, v219
	v_add_f32_e32 v216, v216, v218
	v_mov_b32_e32 v252, v216
	s_nop 1
	v_permlane16_swap_b32_e32 v252, v216
	v_add_f32_e32 v216, v216, v252
	v_mov_b32_e32 v252, v216
	s_nop 1
	v_permlane32_swap_b32_e32 v252, v216
	v_add_f32_e32 v34, v216, v252
	v_fmamk_f32 v34, v34, 0x3a800000, v212
	v_rsq_f32_e32 v224, v34
	s_nop 0
	v_mul_f32_e32 v225, v34, v224
	v_fma_f32 v225, -v225, v224, 1.0
	v_mul_f32_e32 v226, 0.5, v224
	s_nop 0
	v_lshlrev_b64 v[36:37], 13, v[50:51]
	s_nop 0
	v_fma_f32 v34, v226, v225, v224
	v_pk_mul_f32 v[32:33], v[32:33], v[34:35] op_sel_hi:[1,0]
	v_pk_mul_f32 v[30:31], v[30:31], v[34:35] op_sel_hi:[1,0]
	v_pk_mul_f32 v[28:29], v[28:29], v[34:35] op_sel_hi:[1,0]
	v_pk_mul_f32 v[26:27], v[26:27], v[34:35] op_sel_hi:[1,0]
	v_max_f32_e32 v30, 0, v30
	v_max_f32_e32 v26, 0, v26
	v_max_f32_e32 v31, 0, v31
	v_max_f32_e32 v27, 0, v27
	v_max_f32_e32 v32, 0, v32
	v_max_f32_e32 v28, 0, v28
	v_max_f32_e32 v33, 0, v33
	v_max_f32_e32 v29, 0, v29
	v_mul_f32_e32 v30, v30, v30
	v_mul_f32_e32 v35, v26, v26
	v_mul_f32_e32 v26, v31, v31
	v_mul_f32_e32 v31, v27, v27
	v_mul_f32_e32 v27, v32, v32
	v_mul_f32_e32 v32, v28, v28
	v_mul_f32_e32 v28, v33, v33
	v_mul_f32_e32 v29, v29, v29
	v_cvt_pk_bf16_f32 v26, v30, v26
	v_cvt_pk_bf16_f32 v27, v27, v28
	v_cvt_pk_bf16_f32 v28, v35, v31
	v_lshl_add_u64 v[30:31], s[40:41], 0, v[36:37]
	v_cvt_pk_bf16_f32 v29, v32, v29
	s_and_saveexec_b64 s[8:9], s[4:5]
	s_cbranch_execz .LBB0_2457
	v_lshl_add_u64 v[32:33], v[140:141], 1, v[30:31]
	global_store_dwordx4 v[32:33], v[26:29], off nt

.LBB0_2459:
	s_or_b64 exec, exec, s[8:9]
	v_add_u32_e32 v34, 0xb0, v142
	v_ashrrev_i32_e32 v35, 31, v34
	v_lshlrev_b64 v[18:19], 6, v[34:35]
	v_lshl_add_u64 v[30:31], s[18:19], 0, v[18:19]
	s_waitcnt vmcnt(2)
	v_add_f32_e32 v220, v220, v221
	v_add_f32_e32 v222, v222, v223
	v_add_f32_e32 v220, v220, v222
	v_mov_b32_e32 v252, v220
	s_nop 1
	v_permlane16_swap_b32_e32 v252, v220
	v_add_f32_e32 v220, v220, v252
	v_mov_b32_e32 v252, v220
	s_nop 1
	v_permlane32_swap_b32_e32 v252, v220
	v_add_f32_e32 v18, v220, v252
	v_fmamk_f32 v18, v18, 0x3a800000, v212
	v_rsq_f32_e32 v224, v18
	s_nop 0
	v_mul_f32_e32 v225, v18, v224
	v_fma_f32 v225, -v225, v224, 1.0
	v_mul_f32_e32 v226, 0.5, v224
	s_nop 0
	v_lshlrev_b64 v[20:21], 13, v[34:35]
	s_nop 0
	v_fma_f32 v18, v226, v225, v224
	v_pk_mul_f32 v[16:17], v[16:17], v[18:19] op_sel_hi:[1,0]
	v_pk_mul_f32 v[14:15], v[14:15], v[18:19] op_sel_hi:[1,0]
	v_pk_mul_f32 v[12:13], v[12:13], v[18:19] op_sel_hi:[1,0]
	v_pk_mul_f32 v[10:11], v[10:11], v[18:19] op_sel_hi:[1,0]
	v_max_f32_e32 v14, 0, v14
	v_max_f32_e32 v10, 0, v10
	v_max_f32_e32 v15, 0, v15
	v_max_f32_e32 v11, 0, v11
	v_max_f32_e32 v16, 0, v16
	v_max_f32_e32 v12, 0, v12
	v_max_f32_e32 v17, 0, v17
	v_max_f32_e32 v13, 0, v13
	v_mul_f32_e32 v14, v14, v14
	v_mul_f32_e32 v19, v10, v10
	v_mul_f32_e32 v10, v15, v15
	v_mul_f32_e32 v15, v11, v11
	v_mul_f32_e32 v11, v16, v16
	v_mul_f32_e32 v16, v12, v12
	v_mul_f32_e32 v12, v17, v17
	v_mul_f32_e32 v13, v13, v13
	v_cvt_pk_bf16_f32 v10, v14, v10
	v_cvt_pk_bf16_f32 v11, v11, v12
	v_cvt_pk_bf16_f32 v12, v19, v15
	v_lshl_add_u64 v[14:15], s[40:41], 0, v[20:21]
	v_cvt_pk_bf16_f32 v13, v16, v13
	s_and_saveexec_b64 s[8:9], s[4:5]
	s_cbranch_execz .LBB0_2461
	v_lshl_add_u64 v[16:17], v[140:141], 1, v[14:15]
	global_store_dwordx4 v[16:17], v[10:13], off nt
